# no L2 write-back at the P0->P1 barrier (P1 reads only inputs and the atomically accumulated adaLN sums; P0's copies are flushed at the next barrier)
# baseline (speedup 1.0000x reference)
; __device__ __forceinline__ unsigned xb_add(unsigned* p, unsigned v) { return __hip_atomic_fetch_add(p, v, __ATOMIC_RELAXED, __HIP_MEMORY_SCOPE_AGENT); }
; #define GRID_BAR() xcd_barrier(bar)
; #define GRID_BAR() do {} while (0)
; #define BOTH(k) (IN(k) && IN((k) + 1))
; __device__ __forceinline__ void xcd_barrier(const XcdBarrier& b) {
;     asm volatile("s_waitcnt vmcnt(0)" ::: "memory");
;     __syncthreads();
;     if (threadIdx.x == 0) {
;         unsigned* bar = b.bar;
;         __builtin_amdgcn_s_waitcnt(0);
;         unsigned nloc = b.st[0], nx = b.st[1];
;         if (nloc == 0u) { xcd_barrier_complete(bar, b.x, nloc, nx); b.st[0] = nloc; b.st[1] = nx; }
;         const unsigned old = xb_add(&bar[XB_XSUB(b.x)], 1u);
;         const unsigned gen = old / nloc;
;         if (old + 1u == (gen + 1u) * nloc) {
;             __builtin_amdgcn_fence(__ATOMIC_RELEASE, "agent");
;             asm volatile("s_waitcnt vmcnt(0)" ::: "memory");
;             const unsigned og = xb_add(&bar[XB_TOP], 1u);
;             const unsigned tg = og / nx;
;             if (og + 1u == (tg + 1u) * nx) xb_add(&bar[XB_TOPGEN], 1u);
; __global__ void __launch_bounds__(NTHR, 2) fwd_kernel(Args args) {
;     ...
;         if (BOTH(PH_PRO)) GRID_BAR();
.LBB0_120:
	s_waitcnt vmcnt(0)
	s_barrier
	s_and_saveexec_b64 s[4:5], s[84:85]
	s_cbranch_execz .LBB0_172
	s_and_b32 s3, s91, 7
	s_lshl_b32 s3, s3, 7
	s_add_u32 s8, s96, 0x4000
	s_addc_u32 s9, s97, 0
	s_add_u32 s6, s8, s3
	s_addc_u32 s7, s9, 0
	v_mov_b32_e32 v1, 0
	v_mov_b32_e32 v2, 1
	s_mov_b32 s12, 0
	s_waitcnt vmcnt(0) lgkmcnt(0)
	global_atomic_add v3, v1, v2, s[6:7] sc0
	buffer_inv sc1
	s_waitcnt vmcnt(1)
	v_cmp_eq_u32_e32 vcc, 31, v3
	s_cbranch_vccz .Lgb0_poll
	global_atomic_add v1, v2, s[8:9] offset:1024
	global_atomic_add v1, v2, s[8:9] offset:1152
	global_atomic_add v1, v2, s[8:9] offset:1280
	global_atomic_add v1, v2, s[8:9] offset:1408
	global_atomic_add v1, v2, s[8:9] offset:1536
	global_atomic_add v1, v2, s[8:9] offset:1664
	global_atomic_add v1, v2, s[8:9] offset:1792
	global_atomic_add v1, v2, s[8:9] offset:1920
